# q fragments prefetched one task ahead into v240-255 (256 VGPRs) + gating pipelined
# speedup vs baseline: 1.0153x; 1.0153x over previous
.LBB0_340:
	s_ashr_i32 s0, s83, 7
	s_lshl_b32 s1, s83, 9
	s_and_b32 s84, s1, 0xe00
	s_ashr_i32 s1, s0, 31
	s_bfe_u32 s10, s83, 0x40003
	s_lshl_b64 s[34:35], s[0:1], 12
	s_lshl_b32 s0, s0, 4
	s_or_b32 s0, s0, s10
	s_ashr_i32 s1, s0, 31
	s_lshl_b64 s[0:1], s[0:1], 19
	s_add_u32 s40, s6, s0
	s_addc_u32 s41, s7, s1
	s_add_u32 s42, s8, s0
	s_addc_u32 s43, s9, s1
	s_lshl_b32 s0, s83, 3
	s_add_i32 s85, s0, s81
	s_mul_i32 s85, s85, 6
	s_lshl_b32 s10, s10, 7
	s_mov_b32 s86, 0
	v_mbcnt_lo_u32_b32 v0, -1, 0
	v_mbcnt_hi_u32_b32 v0, -1, v0
	v_and_b32_e32 v1, 31, v0
	v_lshrrev_b32_e32 v2, 5, v0
	s_lshl_b32 s12, s73, 5
	s_add_i32 s12, s12, s84
	s_add_i32 s12, s12, s34
	v_add_u32_e32 v1, s12, v1
	v_mul_lo_u32 v1, v1, s75
	v_lshlrev_b32_e32 v2, 4, v2
	v_add3_u32 v1, v2, s10, v1
	global_load_dwordx4 v[240:243], v1, s[28:29]
	global_load_dwordx4 v[244:247], v1, s[28:29] offset:32
	global_load_dwordx4 v[248:251], v1, s[28:29] offset:64
	global_load_dwordx4 v[252:255], v1, s[28:29] offset:96
	s_branch .LBB0_342

.LBB0_344:
	s_or_b32 s14, s0, s73
	s_or_b32 s0, s0, s87
	s_add_i32 s0, s0, s85
	s_lshl_b32 s12, s0, 9
	s_cmpk_gt_i32 s0, 0x1fef
	s_cselect_b64 s[18:19], -1, 0
	s_add_i32 s13, s12, 0xffc02000
	s_and_b64 s[0:1], s[18:19], exec
	s_cselect_b32 s15, s13, s12
	s_mul_hi_i32 s0, s15, 0x80402011
	s_add_i32 s0, s0, s15
	s_lshr_b32 s1, s0, 31
	s_ashr_i32 s0, s0, 18
	s_add_i32 s16, s0, s1
	s_add_i32 s17, s16, 1
	s_and_b64 s[12:13], s[18:19], exec
	v_mbcnt_lo_u32_b32 v172, -1, 0
	v_mbcnt_hi_u32_b32 v172, -1, v172
	s_cselect_b32 s12, s51, s49
	s_cselect_b32 s13, s50, s48
	s_and_b32 s1, s14, s88
	s_lshr_b32 s14, s14, s87
	v_ashrrev_i32_e32 v36, 3, v172
	s_or_b32 s1, s1, s84
	s_lshl_b32 s14, s14, s89
	v_subrev_u32_e32 v37, 64, v36
	s_add_i32 s1, s1, s14
	v_lshlrev_b32_e32 v37, s87, v37
	v_lshlrev_b32_e32 v1, 4, v172
	v_add_u32_e32 v37, s1, v37
	v_and_b32_e32 v41, 0x70, v1
	v_max_i32_e32 v37, 0, v37
	v_lshl_or_b32 v163, v37, 7, v41
	v_subrev_u32_e32 v37, 56, v36
	v_lshlrev_b32_e32 v37, s87, v37
	v_add_u32_e32 v37, s1, v37
	v_max_i32_e32 v37, 0, v37
	v_lshl_or_b32 v165, v37, 7, v41
	v_subrev_u32_e32 v37, 48, v36
	v_lshlrev_b32_e32 v37, s87, v37
	v_add_u32_e32 v37, s1, v37
	v_max_i32_e32 v37, 0, v37
	v_lshl_or_b32 v167, v37, 7, v41
	v_subrev_u32_e32 v37, 40, v36
	v_lshlrev_b32_e32 v37, s87, v37
	v_add_u32_e32 v37, s1, v37
	v_max_i32_e32 v37, 0, v37
	v_lshl_or_b32 v186, v37, 7, v41
	v_subrev_u32_e32 v37, 32, v36
	v_lshlrev_b32_e32 v37, s87, v37
	v_add_u32_e32 v37, s1, v37
	v_max_i32_e32 v37, 0, v37
	v_lshl_or_b32 v144, v37, 7, v41
	v_subrev_u32_e32 v37, 24, v36
	v_lshlrev_b32_e32 v37, s87, v37
	v_add_u32_e32 v37, s1, v37
	v_max_i32_e32 v37, 0, v37
	v_lshl_or_b32 v154, v37, 7, v41
	v_add_lshl_u32 v37, v36, -16, s87
	v_add_u32_e32 v37, s1, v37
	v_max_i32_e32 v37, 0, v37
	v_lshl_or_b32 v156, v37, 7, v41
	v_add_lshl_u32 v37, v36, -8, s87
	v_add_u32_e32 v37, s1, v37
	v_max_i32_e32 v37, 0, v37
	v_lshl_or_b32 v158, v37, 7, v41
	v_lshlrev_b32_e32 v37, s87, v36
	v_add_u32_e32 v37, s1, v37
	v_max_i32_e32 v37, 0, v37
	v_lshl_or_b32 v160, v37, 7, v41
	v_add_lshl_u32 v37, v36, 8, s87
	v_add_u32_e32 v37, s1, v37
	v_max_i32_e32 v37, 0, v37
	v_lshl_or_b32 v162, v37, 7, v41
	v_add_lshl_u32 v37, v36, 16, s87
	v_add_u32_e32 v37, s1, v37
	v_and_b32_e32 v176, 31, v172
	v_max_i32_e32 v37, 0, v37
	v_lshlrev_b32_e32 v0, s87, v176
	v_lshl_or_b32 v164, v37, 7, v41
	v_add_lshl_u32 v37, v36, 24, s87
	s_mul_i32 s0, s17, 0x7fc00
	v_add_u32_e32 v174, s1, v0
	v_add_u32_e32 v37, s1, v37
	v_add_u32_e32 v187, s15, v172
	v_ashrrev_i32_e32 v173, 5, v172
	v_add_u32_e32 v0, s34, v174
	v_max_i32_e32 v37, 0, v37
	v_mov_b32_e32 v188, s17
	v_mov_b32_e32 v189, s16
	v_cmp_gt_i32_e32 vcc, s0, v187
	v_mul_lo_u32 v0, v0, s75
	v_lshlrev_b32_e32 v40, 4, v173
	v_lshl_or_b32 v166, v37, 7, v41
	v_cndmask_b32_e32 v37, v188, v189, vcc
	v_lshlrev_b32_e32 v38, 4, v187
	v_add3_u32 v0, v40, s10, v0
	v_lshl_add_u32 v190, v37, 14, v38
	v_add_u32_e32 v37, 64, v187
	v_add_u32_e32 v0, 0xffffff80, v36
	v_add_u32_e32 v8, 0xffffff90, v36
	v_add_u32_e32 v20, 0xffffffa0, v36
	v_add_u32_e32 v28, 0xffffffb0, v36
	v_cmp_gt_i32_e32 vcc, s0, v37
	v_lshlrev_b32_e32 v0, s87, v0
	v_lshlrev_b32_e32 v8, s87, v8
	v_lshlrev_b32_e32 v20, s87, v20
	v_lshlrev_b32_e32 v28, s87, v28
	v_cndmask_b32_e32 v38, v188, v189, vcc
	v_lshlrev_b32_e32 v37, 4, v37
	v_add_u32_e32 v0, s1, v0
	v_add_u32_e32 v8, s1, v8
	v_add_u32_e32 v20, s1, v20
	v_add_u32_e32 v28, s1, v28
	v_lshl_add_u32 v191, v38, 14, v37
	v_add_u32_e32 v37, 0x80, v187
	v_max_i32_e32 v0, 0, v0
	v_max_i32_e32 v8, 0, v8
	v_max_i32_e32 v20, 0, v20
	v_max_i32_e32 v28, 0, v28
	v_cmp_gt_i32_e32 vcc, s0, v37
	v_lshl_or_b32 v124, v0, 7, v41
	v_add_u32_e32 v0, 0xffffff88, v36
	v_lshl_or_b32 v126, v8, 7, v41
	v_add_u32_e32 v8, 0xffffff98, v36
	v_lshl_or_b32 v155, v20, 7, v41
	v_add_u32_e32 v20, 0xffffffa8, v36
	v_lshl_or_b32 v159, v28, 7, v41
	v_add_u32_e32 v28, 0xffffffb8, v36
	v_cndmask_b32_e32 v38, v188, v189, vcc
	v_lshlrev_b32_e32 v37, 4, v37
	v_lshlrev_b32_e32 v0, s87, v0
	v_lshlrev_b32_e32 v8, s87, v8
	v_lshlrev_b32_e32 v20, s87, v20
	v_lshlrev_b32_e32 v28, s87, v28
	v_lshl_add_u32 v192, v38, 14, v37
	v_add_u32_e32 v37, 0xc0, v187
	s_add_u32 s36, s13, 0x4000
	v_add_u32_e32 v0, s1, v0
	v_add_u32_e32 v8, s1, v8
	v_add_u32_e32 v20, s1, v20
	v_add_u32_e32 v28, s1, v28
	v_cmp_gt_i32_e32 vcc, s0, v37
	s_addc_u32 s37, s12, 0
	v_max_i32_e32 v0, 0, v0
	v_max_i32_e32 v8, 0, v8
	v_max_i32_e32 v20, 0, v20
	v_max_i32_e32 v28, 0, v28
	v_cndmask_b32_e32 v38, v188, v189, vcc
	v_lshlrev_b32_e32 v37, 4, v37
	v_lshl_or_b32 v125, v0, 7, v41
	global_load_dwordx4 v[0:3], v124, s[40:41]
	global_load_dwordx4 v[4:7], v125, s[40:41]
	v_lshl_or_b32 v127, v8, 7, v41
	global_load_dwordx4 v[8:11], v126, s[40:41]
	global_load_dwordx4 v[12:15], v127, s[40:41]
	v_lshl_or_b32 v157, v20, 7, v41
	global_load_dwordx4 v[20:23], v155, s[40:41]
	global_load_dwordx4 v[24:27], v157, s[40:41]
	v_lshl_or_b32 v161, v28, 7, v41
	global_load_dwordx4 v[28:31], v159, s[40:41]
	global_load_dwordx4 v[32:35], v161, s[40:41]
	global_load_dwordx4 v[48:51], v163, s[40:41]
	global_load_dwordx4 v[52:55], v165, s[40:41]
	global_load_dwordx4 v[56:59], v167, s[40:41]
	global_load_dwordx4 v[60:63], v186, s[40:41]
	global_load_dwordx4 v[92:95], v154, s[40:41]
	global_load_dwordx4 v[96:99], v156, s[40:41]
	global_load_dwordx4 v[100:103], v158, s[40:41]
	global_load_dwordx4 v[104:107], v160, s[40:41]
	global_load_dwordx4 v[108:111], v162, s[40:41]
	global_load_dwordx4 v[112:115], v164, s[40:41]
	global_load_dwordx4 v[116:119], v144, s[40:41]
	global_load_dwordx4 v[120:123], v166, s[40:41]
	global_load_dwordx4 v[146:149], v190, s[36:37] nt
	global_load_dwordx4 v[150:153], v191, s[36:37] nt
	v_lshl_add_u32 v193, v38, 14, v37
	global_load_dwordx4 v[178:181], v192, s[36:37] nt
	global_load_dwordx4 v[182:185], v193, s[36:37] nt
	s_and_b64 s[12:13], s[18:19], exec
	s_mov_b32 s12, 0xa05e000
	s_cselect_b32 s12, s12, 0x605e000
	s_add_u32 s18, s66, s12
	v_lshlrev_b32_e32 v177, 2, v173
	s_addc_u32 s19, s67, 0
	v_mul_lo_u32 v43, v36, s76
	v_add_u32_e32 v168, s72, v41
	v_add_u32_e32 v44, 0x480, v43
	v_add_u32_e32 v45, 0x900, v43
	v_add_u32_e32 v46, 0xd80, v43
	v_mul_u32_u24_e32 v42, 0x90, v176
	v_add_u32_e32 v175, v168, v43
	v_add_u32_e32 v128, v168, v44
	v_add_u32_e32 v129, v168, v45
	v_add_u32_e32 v130, v168, v46
	s_waitcnt vmcnt(23)
	ds_write_b128 v175, v[0:3]
	s_waitcnt vmcnt(22)
	ds_write_b128 v128, v[4:7]
	s_waitcnt vmcnt(21)
	ds_write_b128 v129, v[8:11]
	s_waitcnt vmcnt(20)
	ds_write_b128 v130, v[12:15]
	v_add3_u32 v131, s72, v42, v40
	ds_read_b128 v[0:3], v131
	ds_read_b128 v[36:39], v131 offset:32
	s_waitcnt lgkmcnt(1)
	v_mfma_f32_32x32x16_bf16 v[0:15], v[0:3], v[240:243], 0
	v_add_u32_e32 v47, s74, v41
	v_add_u32_e32 v132, v47, v43
	v_add3_u32 v133, s74, v42, v40
	ds_read_b128 v[40:43], v131 offset:96
	v_add_u32_e32 v134, v47, v44
	v_add_u32_e32 v135, v47, v45
	v_add_u32_e32 v136, v47, v46
	s_waitcnt lgkmcnt(1)
	v_mfma_f32_32x32x16_bf16 v[0:15], v[36:39], v[244:247], v[0:15]
	ds_read_b128 v[36:39], v131 offset:64
	s_waitcnt vmcnt(19)
	ds_write_b128 v132, v[20:23]
	s_waitcnt vmcnt(18)
	ds_write_b128 v134, v[24:27]
	s_waitcnt vmcnt(17)
	ds_write_b128 v135, v[28:31]
	s_waitcnt vmcnt(16)
	ds_write_b128 v136, v[32:35]
	ds_read_b128 v[20:23], v133
	s_waitcnt lgkmcnt(5)
	v_mfma_f32_32x32x16_bf16 v[0:15], v[36:39], v[248:251], v[0:15]
	v_mfma_f32_32x32x16_bf16 v[0:15], v[40:43], v[252:255], v[0:15]
	s_waitcnt lgkmcnt(0)
	v_mfma_f32_32x32x16_bf16 v[32:47], v[20:23], v[240:243], 0
	ds_read_b128 v[20:23], v133 offset:32
	s_waitcnt lgkmcnt(0)
	v_mfma_f32_32x32x16_bf16 v[32:47], v[20:23], v[244:247], v[32:47]
	ds_read_b128 v[20:23], v133 offset:64
	s_waitcnt lgkmcnt(0)
	v_mfma_f32_32x32x16_bf16 v[32:47], v[20:23], v[248:251], v[32:47]
	ds_read_b128 v[20:23], v133 offset:96
	s_waitcnt vmcnt(15)
	ds_write_b128 v175, v[48:51]
	s_waitcnt vmcnt(14)
	ds_write_b128 v128, v[52:55]
	s_waitcnt vmcnt(13)
	ds_write_b128 v129, v[56:59]
	s_waitcnt vmcnt(12)
	ds_write_b128 v130, v[60:63]
	s_waitcnt lgkmcnt(4)
	v_mfma_f32_32x32x16_bf16 v[32:47], v[20:23], v[252:255], v[32:47]
	ds_read_b128 v[20:23], v131
	s_waitcnt lgkmcnt(0)
	v_mfma_f32_32x32x16_bf16 v[64:79], v[20:23], v[240:243], 0
	ds_read_b128 v[20:23], v131 offset:32
	s_waitcnt lgkmcnt(0)
	v_mfma_f32_32x32x16_bf16 v[64:79], v[20:23], v[244:247], v[64:79]
	ds_read_b128 v[20:23], v131 offset:64
	s_waitcnt lgkmcnt(0)
	v_mfma_f32_32x32x16_bf16 v[64:79], v[20:23], v[248:251], v[64:79]
	ds_read_b128 v[20:23], v131 offset:96
	s_waitcnt vmcnt(5)
	ds_write_b128 v132, v[116:119]
	ds_write_b128 v134, v[92:95]
	ds_write_b128 v135, v[96:99]
	ds_write_b128 v136, v[100:103]
	s_waitcnt lgkmcnt(4)
	v_mfma_f32_32x32x16_bf16 v[64:79], v[20:23], v[252:255], v[64:79]
	ds_read_b128 v[20:23], v133
	s_waitcnt lgkmcnt(0)
	v_mfma_f32_32x32x16_bf16 v[48:63], v[20:23], v[240:243], 0
	ds_read_b128 v[20:23], v133 offset:32
	s_waitcnt lgkmcnt(0)
	v_mfma_f32_32x32x16_bf16 v[48:63], v[20:23], v[244:247], v[48:63]
	ds_read_b128 v[20:23], v133 offset:64
	s_waitcnt lgkmcnt(0)
	v_mfma_f32_32x32x16_bf16 v[48:63], v[20:23], v[248:251], v[48:63]
	ds_read_b128 v[20:23], v133 offset:96
	ds_write_b128 v175, v[104:107]
	ds_write_b128 v128, v[108:111]
	ds_write_b128 v129, v[112:115]
	s_waitcnt vmcnt(4)
	ds_write_b128 v130, v[120:123]
	ds_read_b128 v[92:95], v131 offset:32
	s_waitcnt lgkmcnt(5)
	v_mfma_f32_32x32x16_bf16 v[48:63], v[20:23], v[252:255], v[48:63]
	ds_read_b128 v[20:23], v131
	s_waitcnt lgkmcnt(0)
	v_mfma_f32_32x32x16_bf16 v[16:31], v[20:23], v[240:243], 0
	v_mfma_f32_32x32x16_bf16 v[16:31], v[92:95], v[244:247], v[16:31]
	ds_read_b128 v[88:91], v131 offset:64
	s_waitcnt lgkmcnt(0)
	v_mfma_f32_32x32x16_bf16 v[16:31], v[88:91], v[248:251], v[16:31]
	ds_read_b128 v[84:87], v131 offset:96
	s_waitcnt lgkmcnt(0)
	v_mfma_f32_32x32x16_bf16 v[16:31], v[84:87], v[252:255], v[16:31]
	global_load_dwordx4 v[140:143], v124, s[42:43]
	global_load_dwordx4 v[136:139], v125, s[42:43]
	global_load_dwordx4 v[132:135], v126, s[42:43]
	global_load_dwordx4 v[128:131], v127, s[42:43]
	global_load_dwordx4 v[112:115], v155, s[42:43]
	global_load_dwordx4 v[116:119], v157, s[42:43]
	global_load_dwordx4 v[120:123], v159, s[42:43]
	s_nop 0
	global_load_dwordx4 v[124:127], v161, s[42:43]
	global_load_dwordx4 v[96:99], v163, s[42:43]
	global_load_dwordx4 v[100:103], v165, s[42:43]
	global_load_dwordx4 v[104:107], v167, s[42:43]
	global_load_dwordx4 v[108:111], v186, s[42:43]
	v_add_u32_e32 v80, 0x100, v187
	v_cmp_gt_i32_e32 vcc, s0, v80
	v_lshlrev_b32_e32 v80, 4, v80
	s_waitcnt vmcnt(15)
	global_store_dwordx4 v190, v[146:149], s[18:19] nt
	s_waitcnt vmcnt(15)
	global_store_dwordx4 v191, v[150:153], s[18:19] nt
	s_waitcnt vmcnt(15)
	global_store_dwordx4 v192, v[178:181], s[18:19] nt
	s_waitcnt vmcnt(15)
	global_store_dwordx4 v193, v[182:185], s[18:19] nt
	v_cndmask_b32_e32 v81, v188, v189, vcc
	v_lshl_add_u32 v146, v81, 14, v80
	v_add_u32_e32 v80, 0x140, v187
	v_cmp_gt_i32_e32 vcc, s0, v80
	v_add_u32_e32 v88, 0x180, v187
	v_lshlrev_b32_e32 v80, 4, v80
	v_cndmask_b32_e32 v81, v188, v189, vcc
	v_cmp_gt_i32_e32 vcc, s0, v88
	v_lshlrev_b32_e32 v88, 4, v88
	v_lshl_add_u32 v148, v81, 14, v80
	v_cndmask_b32_e32 v89, v188, v189, vcc
	v_lshl_add_u32 v150, v89, 14, v88
	v_add_u32_e32 v88, 0x1c0, v187
	v_cmp_gt_i32_e32 vcc, s0, v88
	v_lshlrev_b32_e32 v88, 4, v88
	global_load_dwordx4 v[84:87], v146, s[36:37] nt
	global_load_dwordx4 v[80:83], v148, s[36:37] nt
	v_cndmask_b32_e32 v89, v188, v189, vcc
	v_lshl_add_u32 v152, v89, 14, v88
	global_load_dwordx4 v[92:95], v150, s[36:37] nt
	global_load_dwordx4 v[88:91], v152, s[36:37] nt
	s_add_i32 s13, s86, 1
	s_cmp_lg_u32 s56, 0
	s_cselect_b32 s12, s86, s13
	s_cselect_b32 s14, 1, 0
	s_min_i32 s12, s12, 2
	s_lshl_b32 s13, s12, 1
	s_or_b32 s14, s14, s73
	s_lshl_b32 s15, -1, s13
	s_andn2_b32 s15, s14, s15
	s_or_b32 s15, s15, s84
	s_lshr_b32 s14, s14, s13
	s_add_i32 s17, s13, 5
	s_lshl_b32 s14, s14, s17
	s_add_i32 s15, s15, s14
	s_add_i32 s15, s15, s34
	v_lshlrev_b32_e32 v194, s13, v176
	v_add_u32_e32 v194, s15, v194
	v_mul_lo_u32 v194, v194, s75
	v_lshlrev_b32_e32 v195, 4, v173
	v_add3_u32 v194, v195, s10, v194
	global_load_dwordx4 v[240:243], v194, s[28:29]
	global_load_dwordx4 v[244:247], v194, s[28:29] offset:32
	global_load_dwordx4 v[248:251], v194, s[28:29] offset:64
	global_load_dwordx4 v[252:255], v194, s[28:29] offset:96
	s_ashr_i32 s0, s1, s87
	s_sub_i32 s1, 0x80, s0
	v_max_i32_e32 v147, s1, v176
	v_sub_u32_e32 v147, v147, v177
	v_cmp_gt_i32_e32 vcc, 1, v147
	s_sub_i32 s1, 0x7f, s0
	s_ashr_i32 s1, s1, 5
	v_cndmask_b32_e32 v192, v171, v0, vcc
	v_cmp_gt_i32_e32 vcc, 2, v147
	s_cmpk_lt_i32 s0, 0x80
	s_cselect_b32 s0, s1, -1
	v_cndmask_b32_e32 v190, v171, v1, vcc
	v_cmp_gt_i32_e32 vcc, 3, v147
	s_mov_b32 s1, 0xff800000
	v_max3_f32 v0, v192, s1, v190
	v_cndmask_b32_e32 v193, v171, v2, vcc
	v_cmp_gt_i32_e32 vcc, 4, v147
	s_cmp_lt_i32 s0, 1
	s_mov_b64 s[36:37], -1
	v_cndmask_b32_e32 v191, v171, v3, vcc
	v_cmp_gt_i32_e32 vcc, 9, v147
	v_max3_f32 v0, v0, v193, v191
	s_nop 0
	v_cndmask_b32_e32 v189, v171, v4, vcc
	v_cmp_gt_i32_e32 vcc, 10, v147
	s_nop 1
	v_cndmask_b32_e32 v187, v171, v5, vcc
	v_cmp_gt_i32_e32 vcc, 11, v147
	v_max3_f32 v0, v0, v189, v187
	s_nop 0
	v_cndmask_b32_e32 v188, v171, v6, vcc
	v_cmp_gt_i32_e32 vcc, 12, v147
	s_nop 1
	v_cndmask_b32_e32 v186, v171, v7, vcc
	v_cmp_gt_i32_e32 vcc, 17, v147
	v_max3_f32 v0, v0, v188, v186
	s_nop 0
	v_cndmask_b32_e32 v185, v171, v8, vcc
	v_cmp_gt_i32_e32 vcc, 18, v147
	s_nop 1
	v_cndmask_b32_e32 v183, v171, v9, vcc
	v_cmp_gt_i32_e32 vcc, 19, v147
	v_max3_f32 v0, v0, v185, v183
	s_nop 0
	v_cndmask_b32_e32 v184, v171, v10, vcc
	v_cmp_gt_i32_e32 vcc, 20, v147
	s_nop 1
	v_cndmask_b32_e32 v182, v171, v11, vcc
	v_cmp_gt_i32_e32 vcc, 25, v147
	v_max3_f32 v0, v0, v184, v182
	s_nop 0
	v_cndmask_b32_e32 v181, v171, v12, vcc
	v_cmp_gt_i32_e32 vcc, 26, v147
	s_nop 1
	v_cndmask_b32_e32 v179, v171, v13, vcc
	v_cmp_gt_i32_e32 vcc, 27, v147
	v_max3_f32 v0, v0, v181, v179
	s_nop 0
	v_cndmask_b32_e32 v180, v171, v14, vcc
	v_cmp_gt_i32_e32 vcc, 28, v147
	s_nop 1
	v_cndmask_b32_e32 v178, v171, v15, vcc
	v_max3_f32 v149, v0, v180, v178
	s_cbranch_scc1 .LBB0_346
	v_cmp_gt_i32_e32 vcc, 33, v147
	s_nop 1
	v_cndmask_b32_e32 v0, v171, v32, vcc
	v_cmp_gt_i32_e32 vcc, 34, v147
	s_nop 1
	v_cndmask_b32_e32 v1, v171, v33, vcc
	v_cmp_gt_i32_e32 vcc, 35, v147
	v_max3_f32 v4, v149, v0, v1
	s_nop 0
	v_cndmask_b32_e32 v2, v171, v34, vcc
	v_cmp_gt_i32_e32 vcc, 36, v147
	s_nop 1
	v_cndmask_b32_e32 v3, v171, v35, vcc
	v_cmp_gt_i32_e32 vcc, 41, v147
	v_max3_f32 v6, v4, v2, v3
	s_nop 0
	v_cndmask_b32_e32 v4, v171, v36, vcc
	v_cmp_gt_i32_e32 vcc, 42, v147
	s_nop 1
	v_cndmask_b32_e32 v5, v171, v37, vcc
	v_cmp_gt_i32_e32 vcc, 43, v147
	v_max3_f32 v8, v6, v4, v5
	s_nop 0
	v_cndmask_b32_e32 v6, v171, v38, vcc
	v_cmp_gt_i32_e32 vcc, 44, v147
	s_nop 1
	v_cndmask_b32_e32 v7, v171, v39, vcc
	v_cmp_gt_i32_e32 vcc, 49, v147
	v_max3_f32 v10, v8, v6, v7
	s_nop 0
	v_cndmask_b32_e32 v8, v171, v40, vcc
	v_cmp_gt_i32_e32 vcc, 50, v147
	s_nop 1
	v_cndmask_b32_e32 v9, v171, v41, vcc
	v_cmp_gt_i32_e32 vcc, 51, v147
	v_max3_f32 v12, v10, v8, v9
	s_nop 0
	v_cndmask_b32_e32 v10, v171, v42, vcc
	v_cmp_gt_i32_e32 vcc, 52, v147
	s_nop 1
	v_cndmask_b32_e32 v11, v171, v43, vcc
	v_cmp_gt_i32_e32 vcc, 57, v147
	v_max3_f32 v14, v12, v10, v11
	s_nop 0
	v_cndmask_b32_e32 v12, v171, v44, vcc
	v_cmp_gt_i32_e32 vcc, 58, v147
	s_nop 1
	v_cndmask_b32_e32 v13, v171, v45, vcc
	v_cmp_gt_i32_e32 vcc, 59, v147
	v_max3_f32 v151, v14, v12, v13
	s_nop 0
	v_cndmask_b32_e32 v14, v171, v46, vcc
	v_cmp_gt_i32_e32 vcc, 60, v147
	s_nop 1
	v_cndmask_b32_e32 v15, v171, v47, vcc
	v_max3_f32 v151, v151, v14, v15
	s_cbranch_execnz .LBB0_348
	s_branch .LBB0_347

.LBB0_356:
	v_and_b32_e32 v49, 16, v172
	v_lshlrev_b32_e32 v50, 2, v172
	v_and_or_b32 v49, v50, 12, v49
	v_or_b32_e32 v50, 0x80, v176
	v_sub_u32_e32 v50, v50, v177
	s_movk_i32 s0, 0x7f
	v_cmp_lt_i32_e32 vcc, s0, v50
	s_movk_i32 s0, 0x80
	v_lshrrev_b32_e32 v48, 2, v172
	v_cndmask_b32_e32 v16, v171, v16, vcc
	v_cmp_lt_i32_e32 vcc, s0, v50
	s_movk_i32 s0, 0x81
	v_and_or_b32 v48, v48, 3, v177
	v_cndmask_b32_e32 v17, v171, v17, vcc
	v_cmp_lt_i32_e32 vcc, s0, v50
	s_movk_i32 s0, 0x82
	v_mov_b32_e32 v155, v145
	v_cndmask_b32_e32 v18, v171, v18, vcc
	v_cmp_lt_i32_e32 vcc, s0, v50
	s_movk_i32 s0, 0x87
	v_mov_b32_e32 v157, v145
	v_cndmask_b32_e32 v19, v171, v19, vcc
	v_cmp_lt_i32_e32 vcc, s0, v50
	s_movk_i32 s0, 0x88
	v_mov_b32_e32 v159, v145
	v_cndmask_b32_e32 v20, v171, v20, vcc
	v_cmp_lt_i32_e32 vcc, s0, v50
	s_movk_i32 s0, 0x89
	v_mov_b32_e32 v161, v145
	v_cndmask_b32_e32 v21, v171, v21, vcc
	v_cmp_lt_i32_e32 vcc, s0, v50
	s_movk_i32 s0, 0x8a
	v_mov_b32_e32 v163, v145
	v_cndmask_b32_e32 v22, v171, v22, vcc
	v_cmp_lt_i32_e32 vcc, s0, v50
	s_movk_i32 s0, 0x8f
	v_mov_b32_e32 v165, v145
	v_cndmask_b32_e32 v23, v171, v23, vcc
	v_cmp_lt_i32_e32 vcc, s0, v50
	s_movk_i32 s0, 0x91
	v_mov_b32_e32 v167, v145
	v_cndmask_b32_e32 v24, v171, v24, vcc
	v_cmp_lt_i32_e32 vcc, s76, v50
	v_mov_b32_e32 v147, v145
	v_mov_b32_e32 v149, v145
	v_cndmask_b32_e32 v25, v171, v25, vcc
	v_cmp_lt_i32_e32 vcc, s0, v50
	s_movk_i32 s0, 0x92
	v_mov_b32_e32 v151, v145
	v_cndmask_b32_e32 v26, v171, v26, vcc
	v_cmp_lt_i32_e32 vcc, s0, v50
	s_movk_i32 s0, 0x97
	v_mov_b32_e32 v153, v145
	v_cndmask_b32_e32 v27, v171, v27, vcc
	v_cmp_lt_i32_e32 vcc, s0, v50
	s_movk_i32 s0, 0x98
	v_mul_lo_u32 v48, v48, s76
	v_cndmask_b32_e32 v28, v171, v28, vcc
	v_cmp_lt_i32_e32 vcc, s0, v50
	s_movk_i32 s0, 0x99
	v_lshlrev_b32_e32 v49, 1, v49
	v_cndmask_b32_e32 v29, v171, v29, vcc
	v_cmp_lt_i32_e32 vcc, s0, v50
	s_movk_i32 s0, 0x9a
	s_nop 0
	v_cndmask_b32_e32 v30, v171, v30, vcc
	v_cmp_lt_i32_e32 vcc, s0, v50
	v_max3_f32 v50, v70, v16, v17
	v_max3_f32 v50, v50, v18, v19
	v_max3_f32 v50, v50, v20, v21
	v_max3_f32 v50, v50, v22, v23
	v_max3_f32 v50, v50, v24, v25
	v_max3_f32 v50, v50, v26, v27
	v_cndmask_b32_e32 v31, v171, v31, vcc
	v_max3_f32 v50, v50, v28, v29
	v_max3_f32 v50, v50, v30, v31
	v_mov_b32_e32 v51, v50
	s_nop 1
	v_permlane32_swap_b32_e32 v50, v51
	v_max_f32_e32 v51, v51, v51
	v_max_f32_e32 v50, v50, v50
	v_max_f32_e32 v70, v50, v51
	v_mul_f32_e32 v50, 0x3e38aa3b, v70
	v_fma_f32 v51, v192, s77, -v50
	v_exp_f32_e32 v51, v51
	v_fma_f32 v52, v190, s77, -v50
	v_exp_f32_e32 v52, v52
	v_fma_f32 v53, v193, s77, -v50
	v_exp_f32_e32 v53, v53
	v_fma_f32 v54, v191, s77, -v50
	v_exp_f32_e32 v54, v54
	v_fma_f32 v56, v189, s77, -v50
	v_add_f32_e32 v55, 0, v51
	v_exp_f32_e32 v56, v56
	v_fma_f32 v57, v187, s77, -v50
	v_add_f32_e32 v55, v52, v55
	v_exp_f32_e32 v57, v57
	v_fma_f32 v58, v188, s77, -v50
	v_add_f32_e32 v55, v53, v55
	v_exp_f32_e32 v58, v58
	v_fma_f32 v59, v186, s77, -v50
	v_add_f32_e32 v55, v54, v55
	v_exp_f32_e32 v59, v59
	v_fma_f32 v60, v185, s77, -v50
	v_add_f32_e32 v55, v56, v55
	v_exp_f32_e32 v60, v60
	v_fma_f32 v61, v183, s77, -v50
	v_add_f32_e32 v55, v57, v55
	v_exp_f32_e32 v61, v61
	v_fma_f32 v62, v184, s77, -v50
	v_add_f32_e32 v55, v58, v55
	v_exp_f32_e32 v62, v62
	v_fma_f32 v63, v182, s77, -v50
	v_add_f32_e32 v55, v59, v55
	v_exp_f32_e32 v63, v63
	v_fma_f32 v176, v181, s77, -v50
	v_add_f32_e32 v55, v60, v55
	v_exp_f32_e32 v193, v176
	v_fma_f32 v176, v179, s77, -v50
	v_add_f32_e32 v55, v61, v55
	v_exp_f32_e32 v195, v176
	v_fma_f32 v176, v180, s77, -v50
	v_add_f32_e32 v55, v62, v55
	v_exp_f32_e32 v196, v176
	v_fma_f32 v176, v178, s77, -v50
	v_add_f32_e32 v55, v63, v55
	v_exp_f32_e32 v197, v176
	v_fma_f32 v0, v0, s77, -v50
	v_add_f32_e32 v55, v193, v55
	v_exp_f32_e32 v198, v0
	v_fma_f32 v0, v1, s77, -v50
	v_add_f32_e32 v55, v195, v55
	v_exp_f32_e32 v199, v0
	v_fma_f32 v0, v2, s77, -v50
	v_add_f32_e32 v55, v196, v55
	v_exp_f32_e32 v200, v0
	v_fma_f32 v0, v3, s77, -v50
	v_add_f32_e32 v55, v197, v55
	v_exp_f32_e32 v201, v0
	v_fma_f32 v1, v4, s77, -v50
	v_add_f32_e32 v0, v198, v55
	v_exp_f32_e32 v202, v1
	v_fma_f32 v1, v5, s77, -v50
	v_add_f32_e32 v0, v199, v0
	v_exp_f32_e32 v203, v1
	v_fma_f32 v1, v6, s77, -v50
	v_add_f32_e32 v0, v200, v0
	v_exp_f32_e32 v204, v1
	v_fma_f32 v1, v7, s77, -v50
	v_add_f32_e32 v0, v201, v0
	v_exp_f32_e32 v205, v1
	v_fma_f32 v1, v8, s77, -v50
	v_add_f32_e32 v0, v202, v0
	v_exp_f32_e32 v206, v1
	v_fma_f32 v1, v9, s77, -v50
	v_add_f32_e32 v0, v203, v0
	v_exp_f32_e32 v207, v1
	v_fma_f32 v1, v10, s77, -v50
	v_add_f32_e32 v0, v204, v0
	v_exp_f32_e32 v208, v1
	v_fma_f32 v1, v11, s77, -v50
	v_add_f32_e32 v0, v205, v0
	v_exp_f32_e32 v209, v1
	v_fma_f32 v1, v12, s77, -v50
	v_add_f32_e32 v0, v206, v0
	v_exp_f32_e32 v210, v1
	v_fma_f32 v1, v13, s77, -v50
	v_add_f32_e32 v0, v207, v0
	v_exp_f32_e32 v211, v1
	v_fma_f32 v1, v14, s77, -v50
	v_add_f32_e32 v0, v208, v0
	v_exp_f32_e32 v212, v1
	v_fma_f32 v1, v15, s77, -v50
	v_add_f32_e32 v0, v209, v0
	v_exp_f32_e32 v213, v1
	v_fma_f32 v1, v32, s77, -v50
	v_add_f32_e32 v0, v210, v0
	v_exp_f32_e32 v214, v1
	v_fma_f32 v1, v33, s77, -v50
	v_add_f32_e32 v0, v211, v0
	v_exp_f32_e32 v215, v1
	v_fma_f32 v1, v34, s77, -v50
	v_add_f32_e32 v0, v212, v0
	v_exp_f32_e32 v216, v1
	v_fma_f32 v1, v35, s77, -v50
	v_add_f32_e32 v0, v213, v0
	v_exp_f32_e32 v217, v1
	v_fma_f32 v1, v36, s77, -v50
	v_add_f32_e32 v0, v214, v0
	v_exp_f32_e32 v218, v1
	v_fma_f32 v1, v37, s77, -v50
	v_add_f32_e32 v0, v215, v0
	v_exp_f32_e32 v219, v1
	v_fma_f32 v1, v38, s77, -v50
	v_add_f32_e32 v0, v216, v0
	v_exp_f32_e32 v220, v1
	v_fma_f32 v1, v39, s77, -v50
	v_add_f32_e32 v0, v217, v0
	v_exp_f32_e32 v221, v1
	v_fma_f32 v1, v40, s77, -v50
	v_add_f32_e32 v0, v218, v0
	v_exp_f32_e32 v222, v1
	v_fma_f32 v1, v41, s77, -v50
	v_add_f32_e32 v0, v219, v0
	v_exp_f32_e32 v223, v1
	v_fma_f32 v1, v42, s77, -v50
	v_add_f32_e32 v0, v220, v0
	v_exp_f32_e32 v224, v1
	v_fma_f32 v1, v43, s77, -v50
	v_add_f32_e32 v0, v221, v0
	v_exp_f32_e32 v225, v1
	v_fma_f32 v1, v44, s77, -v50
	v_add_f32_e32 v0, v222, v0
	v_exp_f32_e32 v226, v1
	v_fma_f32 v1, v45, s77, -v50
	v_add_f32_e32 v0, v223, v0
	v_exp_f32_e32 v227, v1
	v_fma_f32 v1, v46, s77, -v50
	v_add_f32_e32 v0, v224, v0
	v_exp_f32_e32 v228, v1
	v_fma_f32 v1, v47, s77, -v50
	v_add_f32_e32 v0, v225, v0
	v_exp_f32_e32 v229, v1
	v_fma_f32 v1, v64, s77, -v50
	v_add_f32_e32 v0, v226, v0
	v_exp_f32_e32 v230, v1
	v_fma_f32 v1, v65, s77, -v50
	v_add_f32_e32 v0, v227, v0
	v_exp_f32_e32 v231, v1
	v_fma_f32 v1, v66, s77, -v50
	v_add_f32_e32 v0, v228, v0
	v_exp_f32_e32 v232, v1
	v_fma_f32 v1, v68, s77, -v50
	v_add_f32_e32 v0, v229, v0
	v_exp_f32_e32 v233, v1
	v_fma_f32 v1, v67, s77, -v50
	v_add_f32_e32 v0, v230, v0
	v_exp_f32_e32 v234, v1
	v_fma_f32 v1, v69, s77, -v50
	v_add_f32_e32 v0, v231, v0
	v_exp_f32_e32 v235, v1
	v_fma_f32 v1, v71, s77, -v50
	v_add_f32_e32 v0, v232, v0
	v_exp_f32_e32 v236, v1
	v_fma_f32 v1, v73, s77, -v50
	v_add_f32_e32 v0, v233, v0
	v_exp_f32_e32 v237, v1
	v_fma_f32 v1, v72, s77, -v50
	v_add_f32_e32 v0, v234, v0
	v_exp_f32_e32 v186, v1
	v_fma_f32 v1, v74, s77, -v50
	v_add_f32_e32 v0, v235, v0
	v_exp_f32_e32 v187, v1
	v_fma_f32 v1, v75, s77, -v50
	v_add_f32_e32 v0, v236, v0
	v_exp_f32_e32 v188, v1
	v_fma_f32 v1, v77, s77, -v50
	v_add_f32_e32 v0, v237, v0
	v_exp_f32_e32 v189, v1
	v_fma_f32 v1, v76, s77, -v50
	v_add_f32_e32 v0, v186, v0
	v_exp_f32_e32 v190, v1
	v_fma_f32 v1, v78, s77, -v50
	v_add_f32_e32 v0, v187, v0
	v_exp_f32_e32 v191, v1
	v_fma_f32 v1, v79, s77, -v50
	v_add_f32_e32 v0, v188, v0
	v_exp_f32_e32 v192, v1
	v_fma_f32 v1, v194, s77, -v50
	v_add_f32_e32 v0, v189, v0
	v_exp_f32_e32 v194, v1
	v_fma_f32 v1, v16, s77, -v50
	v_add_f32_e32 v0, v190, v0
	v_exp_f32_e32 v178, v1
	v_fma_f32 v1, v17, s77, -v50
	v_add_f32_e32 v0, v191, v0
	v_exp_f32_e32 v179, v1
	v_fma_f32 v1, v18, s77, -v50
	v_add_f32_e32 v0, v192, v0
	v_exp_f32_e32 v180, v1
	v_fma_f32 v1, v19, s77, -v50
	v_add_f32_e32 v0, v194, v0
	v_exp_f32_e32 v181, v1
	v_fma_f32 v1, v20, s77, -v50
	v_add_f32_e32 v0, v178, v0
	v_exp_f32_e32 v182, v1
	v_fma_f32 v1, v21, s77, -v50
	v_add_f32_e32 v0, v179, v0
	v_exp_f32_e32 v183, v1
	v_fma_f32 v1, v22, s77, -v50
	v_add_f32_e32 v0, v180, v0
	v_exp_f32_e32 v184, v1
	v_fma_f32 v1, v23, s77, -v50
	v_add_f32_e32 v0, v181, v0
	v_exp_f32_e32 v185, v1
	v_fma_f32 v1, v24, s77, -v50
	v_add_f32_e32 v0, v182, v0
	v_exp_f32_e32 v73, v1
	v_fma_f32 v1, v25, s77, -v50
	v_add_f32_e32 v0, v183, v0
	v_exp_f32_e32 v74, v1
	v_fma_f32 v1, v26, s77, -v50
	v_add_f32_e32 v0, v184, v0
	v_exp_f32_e32 v75, v1
	v_fma_f32 v1, v27, s77, -v50
	v_add_f32_e32 v0, v185, v0
	v_exp_f32_e32 v77, v1
	v_fma_f32 v1, v28, s77, -v50
	v_add_f32_e32 v0, v73, v0
	v_exp_f32_e32 v78, v1
	v_fma_f32 v1, v29, s77, -v50
	v_add_f32_e32 v0, v74, v0
	v_exp_f32_e32 v79, v1
	v_fma_f32 v1, v30, s77, -v50
	v_add_f32_e32 v0, v75, v0
	v_exp_f32_e32 v176, v1
	v_fma_f32 v1, v31, s77, -v50
	v_add_f32_e32 v0, v77, v0
	v_exp_f32_e32 v177, v1
	v_add_f32_e32 v0, v78, v0
	v_add_f32_e32 v0, v79, v0
	v_add_f32_e32 v0, v176, v0
	v_add_f32_e32 v71, v177, v0
	v_mov_b32_e32 v72, v71
	s_nop 1
	v_permlane32_swap_b32_e32 v71, v72
	v_add_u32_e32 v0, 64, v172
	v_lshrrev_b32_e32 v0, 3, v0
	v_mad_u64_u32 v[64:65], s[0:1], v0, s76, v[168:169]
	v_add_u32_e32 v0, 0x80, v172
	v_lshrrev_b32_e32 v0, 3, v0
	v_mad_u64_u32 v[66:67], s[0:1], v0, s76, v[168:169]
	v_add_u32_e32 v0, 0xc0, v172
	v_lshrrev_b32_e32 v0, 3, v0
	v_mad_u64_u32 v[68:69], s[0:1], v0, s76, v[168:169]
	v_add3_u32 v76, s72, v48, v49
	s_waitcnt vmcnt(23)
	ds_write_b128 v175, v[140:143]
	s_waitcnt vmcnt(22)
	ds_write_b128 v64, v[136:139]
	s_waitcnt vmcnt(21)
	ds_write_b128 v66, v[132:135]
	s_waitcnt vmcnt(20)
	ds_write_b128 v68, v[128:131]
	ds_read_b64_tr_b16 v[0:1], v76
	ds_read_b64_tr_b16 v[2:3], v76 offset:1152
	ds_read_b64_tr_b16 v[10:11], v76 offset:1216
	ds_read_b64_tr_b16 v[8:9], v76 offset:64
	v_cvt_pk_bf16_f32 v4, v51, v52
	v_cvt_pk_bf16_f32 v5, v53, v54
	v_cvt_pk_bf16_f32 v6, v56, v57
	v_cvt_pk_bf16_f32 v7, v58, v59
	ds_read_b64_tr_b16 v[32:33], v76 offset:2304
	ds_read_b64_tr_b16 v[34:35], v76 offset:3456
	s_waitcnt lgkmcnt(4)
	v_mfma_f32_32x32x16_bf16 v[16:31], v[0:3], v[4:7], 0
	ds_read_b64_tr_b16 v[42:43], v76 offset:3520
	ds_read_b64_tr_b16 v[40:41], v76 offset:2368
	v_cvt_pk_bf16_f32 v36, v60, v61
	v_cvt_pk_bf16_f32 v37, v62, v63
	v_cvt_pk_bf16_f32 v38, v193, v195
	v_cvt_pk_bf16_f32 v39, v196, v197
	s_waitcnt lgkmcnt(4)
	v_mfma_f32_32x32x16_bf16 v[0:15], v[8:11], v[4:7], 0
	s_waitcnt lgkmcnt(2)
	v_mfma_f32_32x32x16_bf16 v[16:31], v[32:35], v[36:39], v[16:31]
	s_waitcnt lgkmcnt(0)
	v_mfma_f32_32x32x16_bf16 v[0:15], v[40:43], v[36:39], v[0:15]
	v_lshl_add_u64 v[32:33], s[42:43], 0, v[144:145]
	v_lshl_add_u64 v[34:35], s[42:43], 0, v[154:155]
	global_load_dwordx4 v[48:51], v[32:33], off
	global_load_dwordx4 v[52:55], v[34:35], off
	v_lshl_add_u64 v[32:33], s[42:43], 0, v[156:157]
	v_lshl_add_u64 v[34:35], s[42:43], 0, v[158:159]
	global_load_dwordx4 v[56:59], v[32:33], off
	global_load_dwordx4 v[60:63], v[34:35], off
	v_lshl_add_u64 v[32:33], s[42:43], 0, v[160:161]
	v_lshl_add_u64 v[36:37], s[42:43], 0, v[162:163]
	v_lshl_add_u64 v[40:41], s[42:43], 0, v[164:165]
	v_lshl_add_u64 v[44:45], s[42:43], 0, v[166:167]
	global_load_dwordx4 v[32:35], v[32:33], off
	s_nop 0
	global_load_dwordx4 v[36:39], v[36:37], off
	s_nop 0
	global_load_dwordx4 v[40:43], v[40:41], off
	s_nop 0
	global_load_dwordx4 v[44:47], v[44:45], off
	s_waitcnt vmcnt(27)
	ds_write_b128 v175, v[112:115]
	s_waitcnt vmcnt(26)
	ds_write_b128 v64, v[116:119]
	s_waitcnt vmcnt(25)
	ds_write_b128 v66, v[120:123]
	s_waitcnt vmcnt(24)
	ds_write_b128 v68, v[124:127]
	ds_read_b64_tr_b16 v[116:117], v76
	ds_read_b64_tr_b16 v[118:119], v76 offset:1152
	ds_read_b64_tr_b16 v[120:121], v76 offset:64
	ds_read_b64_tr_b16 v[122:123], v76 offset:1216
	v_cvt_pk_bf16_f32 v112, v198, v199
	v_cvt_pk_bf16_f32 v113, v200, v201
	v_cvt_pk_bf16_f32 v114, v202, v203
	v_cvt_pk_bf16_f32 v115, v204, v205
	s_waitcnt lgkmcnt(2)
	s_nop 0
	v_mfma_f32_32x32x16_bf16 v[16:31], v[116:119], v[112:115], v[16:31]
	s_waitcnt lgkmcnt(0)
	v_mfma_f32_32x32x16_bf16 v[0:15], v[120:123], v[112:115], v[0:15]
	ds_read_b64_tr_b16 v[116:117], v76 offset:2304
	ds_read_b64_tr_b16 v[118:119], v76 offset:3456
	ds_read_b64_tr_b16 v[120:121], v76 offset:2368
	ds_read_b64_tr_b16 v[122:123], v76 offset:3520
	v_cvt_pk_bf16_f32 v112, v206, v207
	v_cvt_pk_bf16_f32 v113, v208, v209
	v_cvt_pk_bf16_f32 v114, v210, v211
	v_cvt_pk_bf16_f32 v115, v212, v213
	s_waitcnt lgkmcnt(2)
	s_nop 0
	v_mfma_f32_32x32x16_bf16 v[16:31], v[116:119], v[112:115], v[16:31]
	s_waitcnt lgkmcnt(0)
	v_mfma_f32_32x32x16_bf16 v[0:15], v[120:123], v[112:115], v[0:15]
	s_waitcnt vmcnt(23)
	ds_write_b128 v175, v[96:99]
	s_waitcnt vmcnt(22)
	ds_write_b128 v64, v[100:103]
	s_waitcnt vmcnt(21)
	ds_write_b128 v66, v[104:107]
	s_waitcnt vmcnt(20)
	ds_write_b128 v68, v[108:111]
	ds_read_b64_tr_b16 v[100:101], v76
	ds_read_b64_tr_b16 v[102:103], v76 offset:1152
	ds_read_b64_tr_b16 v[104:105], v76 offset:64
	ds_read_b64_tr_b16 v[106:107], v76 offset:1216
	v_cvt_pk_bf16_f32 v96, v214, v215
	v_cvt_pk_bf16_f32 v97, v216, v217
	v_cvt_pk_bf16_f32 v98, v218, v219
	v_cvt_pk_bf16_f32 v99, v220, v221
	s_waitcnt lgkmcnt(2)
	s_nop 0
	v_mfma_f32_32x32x16_bf16 v[16:31], v[100:103], v[96:99], v[16:31]
	s_waitcnt lgkmcnt(0)
	v_mfma_f32_32x32x16_bf16 v[0:15], v[104:107], v[96:99], v[0:15]
	ds_read_b64_tr_b16 v[100:101], v76 offset:2304
	ds_read_b64_tr_b16 v[102:103], v76 offset:3456
	ds_read_b64_tr_b16 v[104:105], v76 offset:2368
	ds_read_b64_tr_b16 v[106:107], v76 offset:3520
	v_cvt_pk_bf16_f32 v96, v222, v223
	v_cvt_pk_bf16_f32 v97, v224, v225
	v_cvt_pk_bf16_f32 v98, v226, v227
	v_cvt_pk_bf16_f32 v99, v228, v229
	s_waitcnt lgkmcnt(2)
	s_nop 0
	v_mfma_f32_32x32x16_bf16 v[16:31], v[100:103], v[96:99], v[16:31]
	s_waitcnt lgkmcnt(0)
	v_mfma_f32_32x32x16_bf16 v[0:15], v[104:107], v[96:99], v[0:15]
	s_waitcnt vmcnt(7)
	ds_write_b128 v175, v[48:51]
	s_waitcnt vmcnt(6)
	ds_write_b128 v64, v[52:55]
	s_waitcnt vmcnt(5)
	ds_write_b128 v66, v[56:59]
	s_waitcnt vmcnt(4)
	ds_write_b128 v68, v[60:63]
	ds_read_b64_tr_b16 v[52:53], v76
	ds_read_b64_tr_b16 v[54:55], v76 offset:1152
	ds_read_b64_tr_b16 v[56:57], v76 offset:64
	ds_read_b64_tr_b16 v[58:59], v76 offset:1216
	v_cvt_pk_bf16_f32 v48, v230, v231
	v_cvt_pk_bf16_f32 v49, v232, v233
	v_cvt_pk_bf16_f32 v50, v234, v235
	v_cvt_pk_bf16_f32 v51, v236, v237
	s_waitcnt lgkmcnt(2)
	s_nop 0
	v_mfma_f32_32x32x16_bf16 v[16:31], v[52:55], v[48:51], v[16:31]
	s_waitcnt lgkmcnt(0)
	v_mfma_f32_32x32x16_bf16 v[0:15], v[56:59], v[48:51], v[0:15]
	ds_read_b64_tr_b16 v[52:53], v76 offset:2304
	ds_read_b64_tr_b16 v[54:55], v76 offset:3456
	ds_read_b64_tr_b16 v[56:57], v76 offset:2368
	ds_read_b64_tr_b16 v[58:59], v76 offset:3520
	v_cvt_pk_bf16_f32 v48, v186, v187
	v_cvt_pk_bf16_f32 v49, v188, v189
	v_cvt_pk_bf16_f32 v50, v190, v191
	v_cvt_pk_bf16_f32 v51, v192, v194
	s_waitcnt lgkmcnt(2)
	s_nop 0
	v_mfma_f32_32x32x16_bf16 v[16:31], v[52:55], v[48:51], v[16:31]
	s_waitcnt lgkmcnt(0)
	v_mfma_f32_32x32x16_bf16 v[0:15], v[56:59], v[48:51], v[0:15]
	s_waitcnt vmcnt(3)
	ds_write_b128 v175, v[32:35]
	s_waitcnt vmcnt(2)
	ds_write_b128 v64, v[36:39]
	s_waitcnt vmcnt(1)
	ds_write_b128 v66, v[40:43]
	s_waitcnt vmcnt(0)
	ds_write_b128 v68, v[44:47]
	ds_read_b64_tr_b16 v[36:37], v76
	ds_read_b64_tr_b16 v[38:39], v76 offset:1152
	ds_read_b64_tr_b16 v[40:41], v76 offset:64
	ds_read_b64_tr_b16 v[42:43], v76 offset:1216
	v_cvt_pk_bf16_f32 v32, v178, v179
	v_cvt_pk_bf16_f32 v33, v180, v181
	v_cvt_pk_bf16_f32 v34, v182, v183
	v_cvt_pk_bf16_f32 v35, v184, v185
	s_waitcnt lgkmcnt(2)
	s_nop 0
	v_mfma_f32_32x32x16_bf16 v[16:31], v[36:39], v[32:35], v[16:31]
	s_waitcnt lgkmcnt(0)
	v_mfma_f32_32x32x16_bf16 v[0:15], v[40:43], v[32:35], v[0:15]
	ds_read_b64_tr_b16 v[36:37], v76 offset:2304
	ds_read_b64_tr_b16 v[38:39], v76 offset:3456
	ds_read_b64_tr_b16 v[40:41], v76 offset:2368
	ds_read_b64_tr_b16 v[42:43], v76 offset:3520
	v_cvt_pk_bf16_f32 v32, v73, v74
	v_cvt_pk_bf16_f32 v33, v75, v77
	v_cvt_pk_bf16_f32 v35, v176, v177
	v_cvt_pk_bf16_f32 v34, v78, v79
	s_waitcnt lgkmcnt(2)
	s_nop 0
	v_mfma_f32_32x32x16_bf16 v[16:31], v[36:39], v[32:35], v[16:31]
	v_lshl_add_u64 v[44:45], s[18:19], 0, v[146:147]
	global_store_dwordx4 v[44:45], v[84:87], off nt
	v_lshl_add_u64 v[44:45], s[18:19], 0, v[148:149]
	global_store_dwordx4 v[44:45], v[80:83], off nt
	v_lshl_add_u64 v[44:45], s[18:19], 0, v[150:151]
	global_store_dwordx4 v[44:45], v[92:95], off nt
	v_lshl_add_u64 v[44:45], s[18:19], 0, v[152:153]
	s_waitcnt lgkmcnt(0)
	v_mfma_f32_32x32x16_bf16 v[0:15], v[40:43], v[32:35], v[0:15]
	v_add_f32_e32 v33, v71, v72
	v_div_scale_f32 v32, s[0:1], v33, v33, 1.0
	v_rcp_f32_e32 v34, v32
	global_store_dwordx4 v[44:45], v[88:91], off nt
	v_fma_f32 v35, -v32, v34, 1.0
	v_fmac_f32_e32 v34, v35, v34
	v_div_scale_f32 v35, vcc, 1.0, v33, 1.0
	v_mul_f32_e32 v36, v35, v34
	v_fma_f32 v37, -v32, v36, v35
	v_fmac_f32_e32 v36, v37, v34
	v_fma_f32 v32, -v32, v36, v35
	v_log_f32_e32 v35, v33
	v_div_fmas_f32 v32, v32, v34, v36
	v_div_fixup_f32 v32, v32, v33, 1.0
	v_subrev_u32_e32 v33, s84, v174
	v_cndmask_b32_e64 v34, 0, 1, s[54:55]
	v_fmac_f32_e32 v35, 0x3e38aa3b, v70
	v_cmp_ne_u32_e64 s[38:39], 1, v34
	s_andn2_b64 vcc, exec, s[54:55]
	v_lshl_add_u32 v36, v33, 2, 0
	s_cbranch_vccnz .LBB0_358
	v_add_u32_e32 v34, 0x12000, v36
	ds_read_b32 v34, v34
	v_max_f32_e32 v37, v35, v35
	s_waitcnt lgkmcnt(0)
	v_max_f32_e32 v38, v34, v34
	v_max_f32_e32 v37, v38, v37
	v_sub_f32_e32 v38, v34, v37
	v_sub_f32_e32 v39, v35, v37
	v_exp_f32_e32 v38, v38
	v_exp_f32_e32 v39, v39
	s_nop 0
	v_add_f32_e32 v38, v38, v39
	v_log_f32_e32 v38, v38
	s_nop 0
	v_add_f32_e32 v37, v37, v38
	v_sub_f32_e32 v35, v35, v37
	v_exp_f32_e32 v35, v35
	v_sub_f32_e32 v34, v34, v37
	v_exp_f32_e32 v34, v34
	v_mul_f32_e32 v32, v32, v35
	v_mov_b32_e32 v35, v37
	s_branch .LBB0_359

	.amdhsa_kernel _Z9hymba_fwd4Args
		.amdhsa_group_segment_fixed_size 0
		.amdhsa_private_segment_fixed_size 0
		.amdhsa_kernarg_size 360
		.amdhsa_user_sgpr_count 2
		.amdhsa_user_sgpr_dispatch_ptr 0
		.amdhsa_user_sgpr_queue_ptr 0
		.amdhsa_user_sgpr_kernarg_segment_ptr 1
		.amdhsa_user_sgpr_dispatch_id 0
		.amdhsa_user_sgpr_kernarg_preload_length 0
		.amdhsa_user_sgpr_kernarg_preload_offset 0
		.amdhsa_user_sgpr_private_segment_size 0
		.amdhsa_uses_dynamic_stack 0
		.amdhsa_enable_private_segment 0
		.amdhsa_system_sgpr_workgroup_id_x 1
		.amdhsa_system_sgpr_workgroup_id_y 0
		.amdhsa_system_sgpr_workgroup_id_z 0
		.amdhsa_system_sgpr_workgroup_info 0
		.amdhsa_system_vgpr_workitem_id 2
		.amdhsa_next_free_vgpr 256
		.amdhsa_next_free_sgpr 100
		.amdhsa_accum_offset 256
		.amdhsa_reserve_vcc 1
		.amdhsa_float_round_mode_32 0
		.amdhsa_float_round_mode_16_64 0
		.amdhsa_float_denorm_mode_32 3
		.amdhsa_float_denorm_mode_16_64 3
		.amdhsa_dx10_clamp 1
		.amdhsa_ieee_mode 1
		.amdhsa_fp16_overflow 0
		.amdhsa_tg_split 0
		.amdhsa_exception_fp_ieee_invalid_op 0
		.amdhsa_exception_fp_denorm_src 0
		.amdhsa_exception_fp_ieee_div_zero 0
		.amdhsa_exception_fp_ieee_overflow 0
		.amdhsa_exception_fp_ieee_underflow 0
		.amdhsa_exception_fp_ieee_inexact 0
		.amdhsa_exception_int_div_zero 0
	.end_amdhsa_kernel

.Lfunc_end0:
	.size	_Z9hymba_fwd4Args, .Lfunc_end0-_Z9hymba_fwd4Args
	.set _Z9hymba_fwd4Args.num_vgpr, 256
	.set _Z9hymba_fwd4Args.num_agpr, 0
	.set _Z9hymba_fwd4Args.numbered_sgpr, 100
	.set _Z9hymba_fwd4Args.num_named_barrier, 0
	.set _Z9hymba_fwd4Args.private_seg_size, 0
	.set _Z9hymba_fwd4Args.uses_vcc, 1
	.set _Z9hymba_fwd4Args.uses_flat_scratch, 0
	.set _Z9hymba_fwd4Args.has_dyn_sized_stack, 0
	.set _Z9hymba_fwd4Args.has_recursion, 0
	.set _Z9hymba_fwd4Args.has_indirect_call, 0

amdhsa.kernels:
  - .agpr_count:     0
    .args:
      - .offset:         0
        .size:           104
        .value_kind:     by_value
      - .offset:         104
        .size:           4
        .value_kind:     hidden_block_count_x
      - .offset:         108
        .size:           4
        .value_kind:     hidden_block_count_y
      - .offset:         112
        .size:           4
        .value_kind:     hidden_block_count_z
      - .offset:         116
        .size:           2
        .value_kind:     hidden_group_size_x
      - .offset:         118
        .size:           2
        .value_kind:     hidden_group_size_y
      - .offset:         120
        .size:           2
        .value_kind:     hidden_group_size_z
      - .offset:         122
        .size:           2
        .value_kind:     hidden_remainder_x
      - .offset:         124
        .size:           2
        .value_kind:     hidden_remainder_y
      - .offset:         126
        .size:           2
        .value_kind:     hidden_remainder_z
      - .offset:         144
        .size:           8
        .value_kind:     hidden_global_offset_x
      - .offset:         152
        .size:           8
        .value_kind:     hidden_global_offset_y
      - .offset:         160
        .size:           8
        .value_kind:     hidden_global_offset_z
      - .offset:         168
        .size:           2
        .value_kind:     hidden_grid_dims
      - .offset:         192
        .size:           8
        .value_kind:     hidden_multigrid_sync_arg
      - .offset:         224
        .size:           4
        .value_kind:     hidden_dynamic_lds_size
    .group_segment_fixed_size: 0
    .kernarg_segment_align: 8
    .kernarg_segment_size: 360
    .language:       OpenCL C
    .language_version:
      - 2
      - 0
    .max_flat_workgroup_size: 512
    .name:           _Z9hymba_fwd4Args
    .private_segment_fixed_size: 0
    .sgpr_count:     106
    .sgpr_spill_count: 83
    .symbol:         _Z9hymba_fwd4Args.kd
    .uniform_work_group_size: 1
    .uses_dynamic_stack: false
    .vgpr_count:     256
    .vgpr_spill_count: 0
    .wavefront_size: 64
